# attention: next item's first K/V tile is prefetched at the start of the epilogue and the state init runs under the prologue load latency; tile loop unchanged and at the same code phase
# baseline (speedup 1.0000x reference)
; __device__ __forceinline__ int v_st(int k, int c) { const int kk = (k & ~0xC) | ((k & 4) << 1) | ((k & 8) >> 1); return ((kk >> 3) * 4 + (c >> 5)) * 512 + ((kk & 7) * 32 + (c & 31)) * 2; }
; __device__ __forceinline__ int v_rd_base(int lane) { return ((lane & 3) << 3) | (((lane >> 2) & 3) << 6) | (((lane >> 4) & 1) << 5) | (((lane >> 5) & 1) << 8); }
; __device__ __forceinline__ void attn_body(const bf16_t* __restrict__ Qb, const bf16_t* __restrict__ KVh, const bf16_t* __restrict__ KR, const float* __restrict__ ropeq,
;                                           bf16_t* __restrict__ Ob, int seq, char* lds, const int tid) {
;     ...
;     const int sr = tid >> 4, c16 = tid & 15;
;     const bool isK = c16 < 8;
;     const int kst0 = KSWZ(sr, c16 * 16), kst1 = KSWZ(32 + sr, c16 * 16), vst0 = v_st(sr, (c16 & 7) * 8), vst1 = v_st(32 + sr, (c16 & 7) * 8);
;     const int rkey = (tid & 255) >> 2, rch = tid & 3; const int rst = KSWZ(rkey, 128 + rch * 16); const bool rwr = tid < 256;
;     const int vb0 = (int)(uintptr_t)V_lds + v_rd_base(lane);
; __device__ __forceinline__ void phase_attn(const Ctx& C, PP p, char* lds_generic) {
;     ...
;     for (int it = C.vcu; it < 2048; it += C.G) {
;         const int qb = it & 15, h = (it >> 4) & 15, b = it >> 8; const size_t t0 = (size_t)b * SEQ, q0 = t0 + qb * 256;
;         __syncthreads();
;         att::attn_body(Q + q0 * NQ + h * 96, KV + t0 * NKV + h * 128, KR + t0 * 32, rope + q0 * 32, O + q0 * DM + h * 64, SEQ, lds_generic, C.tid);
.LBB0_39:
	s_andn2_b64 vcc, exec, s[0:1]
	s_cbranch_vccnz .LBB0_79
	s_cmpk_gt_i32 s89, 0x3ff
	s_cbranch_scc1 .LBB0_78
	v_and_b32_e32 v2, 0x3fffffc0, v140
	s_add_i32 s0, 0, 0x18000
	v_lshl_add_u32 v139, v2, 2, s0
	v_ashrrev_i32_e32 v3, 1, v140
	s_movk_i32 s0, 0xffe0
	v_bfi_b32 v4, s0, v3, v140
	s_movk_i32 s0, 0xc00
	v_mad_i64_i32 v[130:131], s[0:1], v4, s0, 0
	v_ashrrev_i32_e32 v5, 31, v4
	v_readlane_b32 s0, v253, 43
	v_lshlrev_b64 v[4:5], 7, v[4:5]
	v_readlane_b32 s1, v253, 44
	v_and_b32_e32 v64, 32, v211
	v_and_b32_e32 v2, 0xffffffe0, v3
	v_lshl_add_u64 v[4:5], s[0:1], 0, v[4:5]
	v_lshl_add_u64 v[132:133], v[4:5], 0, v[64:65]
	v_ashrrev_i32_e32 v4, 4, v140
	v_and_b32_e32 v3, 15, v140
	v_lshlrev_b32_e32 v5, 8, v4
	v_lshlrev_b32_e32 v7, 4, v3
	v_and_b32_e32 v9, 0x70, v140
	v_add_u32_e32 v8, 32, v4
	v_bitop3_b32 v141, v7, v5, v9 bitop3:0xde
	v_lshlrev_b32_e32 v5, 8, v8
	v_bitop3_b32 v182, v5, v7, v9 bitop3:0xf6
	v_and_b32_e32 v5, 0xfffff0, v4
	v_lshlrev_b32_e32 v9, 1, v4
	v_and_or_b32 v5, v9, 8, v5
	v_lshrrev_b32_e32 v9, 1, v4
	v_lshrrev_b32_e32 v5, 1, v5
	v_bfe_u32 v10, v140, 2, 1
	v_and_b32_e32 v11, 3, v4
	v_or_b32_e32 v5, v5, v10
	v_and_or_b32 v9, v9, 4, v11
	v_lshlrev_b32_e32 v11, 4, v140
	v_lshlrev_b32_e32 v5, 9, v5
	v_lshlrev_b32_e32 v9, 6, v9
	v_and_b32_e32 v12, 48, v11
	v_or3_b32 v183, v5, v9, v12
	v_and_b32_e32 v5, 0xfffff0, v8
	v_lshlrev_b32_e32 v13, 1, v8
	v_and_or_b32 v5, v13, 8, v5
	v_lshrrev_b32_e32 v5, 1, v5
	v_or_b32_e32 v5, v5, v10
	v_lshlrev_b32_e32 v5, 9, v5
	v_or3_b32 v184, v5, v9, v12
	v_bfe_u32 v12, v140, 2, 6
	v_and_b32_e32 v13, 3, v140
	v_mov_b32_e32 v9, 0x80
	v_lshlrev_b32_e32 v10, 2, v140
	v_lshlrev_b32_e32 v5, 8, v12
	v_lshl_or_b32 v9, v13, 4, v9
	v_and_b32_e32 v10, 0x70, v10
	v_bitop3_b32 v14, v9, v5, v10 bitop3:0xde
	v_lshlrev_b32_e32 v9, 4, v211
	v_lshlrev_b32_e32 v5, 3, v211
	v_and_b32_e32 v9, 0xc0, v9
	v_lshlrev_b32_e32 v10, 1, v211
	v_lshrrev_b32_e32 v1, 5, v211
	v_and_or_b32 v9, v5, 24, v9
	v_and_b32_e32 v10, 32, v10
	v_and_b32_e32 v5, 0x100, v5
	v_and_b32_e32 v0, 31, v140
	v_or3_b32 v15, v9, v10, v5
	v_ashrrev_i32_e32 v5, 31, v4
	v_ashrrev_i32_e32 v9, 31, v8
	v_lshlrev_b32_e32 v187, 4, v1
	v_lshlrev_b64 v[134:135], 12, v[4:5]
	v_lshlrev_b64 v[142:143], 12, v[8:9]
	v_lshlrev_b32_e32 v5, 8, v0
	v_and_b32_e32 v8, 0x70, v11
	v_or_b32_e32 v9, 32, v187
	v_bitop3_b32 v189, v9, v5, v8 bitop3:0xde
	v_or_b32_e32 v9, 64, v187
	v_bitop3_b32 v212, v9, v5, v8 bitop3:0xde
	v_or_b32_e32 v9, 0x60, v187
	s_cmp_lg_u32 0, -1
	v_lshlrev_b32_e32 v4, 3, v13
	v_bitop3_b32 v213, v9, v5, v8 bitop3:0xde
	v_or_b32_e32 v9, 0x80, v187
	s_mov_b64 s[4:5], 0x40000
	s_cselect_b32 s6, 0, 0
	v_lshl_or_b32 v4, v12, 5, v4
	v_bitop3_b32 v214, v9, v5, v8 bitop3:0xde
	v_or_b32_e32 v9, 0xa0, v187
	v_lshl_add_u64 v[144:145], v[134:135], 0, s[4:5]
	s_mov_b64 s[4:5], 0x60000
	s_add_i32 s7, 0, 0xc000
	v_lshlrev_b32_e32 v6, 3, v1
	v_cmp_lt_u32_e64 s[0:1], 7, v3
	s_movk_i32 s2, 0x100
	v_add_u32_e32 v185, s6, v15
	v_lshlrev_b32_e32 v10, 3, v3
	v_bitop3_b32 v188, v187, v5, v8 bitop3:0xde
	v_bitop3_b32 v215, v9, v5, v8 bitop3:0xde
	v_lshl_add_u64 v[146:147], v[134:135], 0, s[4:5]
	s_mov_b64 s[4:5], 0xa0000
	v_mov_b32_e32 v5, s7
	v_cmp_gt_u32_e32 vcc, 8, v3
	s_add_i32 s6, s6, 0x8000
	v_ashrrev_i32_e32 v3, 31, v2
	v_lshlrev_b32_e32 v154, 13, v1
	v_lshlrev_b32_e32 v1, 1, v4
	v_cmp_gt_i32_e64 s[2:3], s2, v140
	v_add_u32_e32 v186, 0, v14
	v_lshl_add_u64 v[148:149], v[134:135], 0, s[56:57]
	v_lshl_add_u64 v[150:151], v[134:135], 0, s[4:5]
	v_cmp_gt_u32_e64 s[4:5], 32, v211
	v_lshl_add_u32 v216, v0, 2, v139
	v_cndmask_b32_e32 v217, 0, v5, vcc
	v_cndmask_b32_e32 v218, v183, v141, vcc
	v_cndmask_b32_e32 v219, v184, v182, vcc
	v_add_u32_e32 v220, s6, v15
	v_lshlrev_b64 v[152:153], 11, v[2:3]
	v_mov_b32_e32 v155, v65
	v_or_b32_e32 v156, v134, v7
	v_mov_b32_e32 v157, v135
	v_or_b32_e32 v158, 0x1d404000, v1
	v_mov_b32_e32 v159, v65
	v_or_b32_e32 v160, 0x1d403000, v1
	v_mov_b32_e32 v161, v65
	v_lshlrev_b32_e32 v64, 1, v6
	v_lshlrev_b32_e32 v162, 1, v10
	v_lshlrev_b32_e32 v164, 1, v4
	v_lshlrev_b32_e32 v166, 1, v0
	v_mov_b32_e32 v232, v139
	v_mov_b32_e32 v233, v187
	v_mov_b32_e32 v234, v216
	v_mov_b32_e32 v235, v185
	v_mov_b32_e32 v236, v188
	v_mov_b32_e32 v237, v189
	v_mov_b32_e32 v238, v212
	v_mov_b32_e32 v239, v213
	v_mov_b32_e32 v242, v186
	v_add_u32_e32 v240, v217, v218
	v_add_u32_e32 v241, v217, v219
	v_lshrrev_b32_e32 v245, 4, v140
	v_and_b32_e32 v246, 15, v140
	v_lshlrev_b32_e32 v243, 12, v245
	v_lshl_or_b32 v243, v246, 4, v243
	v_and_b32_e32 v245, 0xff, v140
	v_lshlrev_b32_e32 v244, 4, v245
	v_readfirstlane_b32 s23, v140
	s_lshr_b32 s23, s23, 6
	s_load_dwordx2 s[26:27], s[94:95], 0xb8
	s_mov_b32 s20, s89
	s_waitcnt lgkmcnt(0)
	s_mov_b32 s47, 0
.LA_item:
	s_and_b32 s21, s20, 7
	s_lshr_b32 s10, s20, 3
	s_and_b32 s10, s10, 15
	s_lshr_b32 s11, s20, 7
	s_lshl_b32 s12, s11, 12
	s_lshl_b32 s13, s21, 9
	s_add_u32 s12, s12, s13
	s_lshl_b32 s13, s23, 6
	s_add_u32 s12, s12, s13
	s_mul_i32 s14, s12, 0xc00
	s_mul_i32 s15, s10, 0xc0
	s_add_u32 s14, s14, s15
	s_add_u32 s14, s14, 0xac00000
	s_add_u32 s30, s26, s14
	s_addc_u32 s31, s27, 0
	s_lshl_b32 s14, s12, 7
	s_add_u32 s14, s14, 0x100000
	s_add_u32 s40, s26, s14
	s_addc_u32 s41, s27, 0
	s_lshl_b32 s14, s12, 11
	s_lshl_b32 s15, s10, 7
	s_add_u32 s14, s14, s15
	s_add_u32 s14, s14, 0x6c00000
	s_add_u32 s42, s26, s14
	s_addc_u32 s43, s27, 0
	s_lshl_b32 s14, s11, 24
	s_lshl_b32 s15, s10, 8
	s_add_u32 s14, s14, s15
	s_add_u32 s14, s14, 0x10c00000
	s_add_u32 s28, s26, s14
	s_addc_u32 s29, s27, 0
	s_lshl_b32 s14, s11, 18
	s_add_u32 s14, s14, 0x1d400000
	s_add_u32 s44, s26, s14
	s_addc_u32 s45, s27, 0
	s_barrier
	s_cmp_eq_u32 s47, 0
	s_cbranch_scc1 .LA_pf0
	s_add_u32 s28, s28, 0x40000
	s_addc_u32 s29, s29, 0
	s_add_u32 s44, s44, 0x1000
	s_addc_u32 s45, s45, 0
	s_branch .LA_pf1

; __device__ __forceinline__ unsigned pk2(float lo, float hi) { return f2bf(lo) | (f2bf(hi) << 16); }
; #define SLOAD(i, k0) do { sr_[i].a0 = *reinterpret_cast<const bf16x8*>(&KVh[(size_t)((k0) + sr) * NKV + c16 * 8]); sr_[i].a1 = *reinterpret_cast<const bf16x8*>(&KVh[(size_t)((k0) + 32 + sr) * NKV + c16 * 8]); \
;     sr_[i].rr = *reinterpret_cast<const bf16x8*>(&KR[(size_t)((k0) + rkey) * 32 + rch * 8]); } while (0)
; #define SWRITE(b, i) do { if (isK) { *(bf16x8*)(K_lds + (b) * SHM_K + kst0) = sr_[i].a0; *(bf16x8*)(K_lds + (b) * SHM_K + kst1) = sr_[i].a1; } \
;     else { *(bf16x8*)(V_lds + (b) * SHM_V + vst0) = sr_[i].a0; *(bf16x8*)(V_lds + (b) * SHM_V + vst1) = sr_[i].a1; } \
;     if (rwr) *(bf16x8*)(K_lds + (b) * SHM_K + rst) = sr_[i].rr; } while (0)
; __device__ __forceinline__ void attn_body(const bf16_t* __restrict__ Qb, const bf16_t* __restrict__ KVh, const bf16_t* __restrict__ KR, const float* __restrict__ ropeq,
;                                           bf16_t* __restrict__ Ob, int seq, char* lds, const int tid) {
;     ...
;     { const bf16_t* Qw = Qb + (size_t)(wid * QBLK + r32) * NQ + hi * 8;
; #pragma unroll
;       for (int d0 = 0; d0 < 4; ++d0) qr[d0] = *reinterpret_cast<const bf16x8*>(Qw + d0 * 16);
;       const u32x4 w1 = *reinterpret_cast<const u32x4*>(Qw + 64), w2 = *reinterpret_cast<const u32x4*>(Qw + 80);
;       float x1[8], x2[8]; unpack8(w1, x1); unpack8(w2, x2);
;       const float* rp = ropeq + (size_t)(wid * QBLK + r32) * 32 + hi * 8;
;       float y1[8], y2[8];
; #pragma unroll
;       for (int e = 0; e < 8; ++e) { const float c = rp[e], s = rp[16 + e]; y1[e] = x1[e] * c - x2[e] * s; y2[e] = x1[e] * s + x2[e] * c; }
;       u32x4 o1 = {pk2(y1[0], y1[1]), pk2(y1[2], y1[3]), pk2(y1[4], y1[5]), pk2(y1[6], y1[7])};
;       u32x4 o2 = {pk2(y2[0], y2[1]), pk2(y2[2], y2[3]), pk2(y2[4], y2[5]), pk2(y2[6], y2[7])};
;       qr[4] = *reinterpret_cast<bf16x8*>(&o1); qr[5] = *reinterpret_cast<bf16x8*>(&o2); }
;     ...
;     SLOAD(SE, 0); asm volatile("s_waitcnt vmcnt(0)" ::: "memory"); SWRITE(0, SE); __syncthreads();
.LA_pf1:
	v_and_b32_e32 v245, 31, v211
	v_lshrrev_b32_e32 v246, 5, v211
	v_mul_u32_u24_e32 v247, 0xc00, v245
	v_lshl_add_u32 v247, v246, 4, v247
	v_lshlrev_b32_e32 v202, 7, v245
	v_lshl_add_u32 v202, v246, 5, v202
	global_load_dwordx4 v[142:145], v247, s[30:31] offset:0
	global_load_dwordx4 v[146:149], v247, s[30:31] offset:32
	global_load_dwordx4 v[150:153], v247, s[30:31] offset:64
	global_load_dwordx4 v[154:157], v247, s[30:31] offset:96
	global_load_dwordx4 v[158:161], v247, s[30:31] offset:128
	global_load_dwordx4 v[162:165], v247, s[30:31] offset:160
	global_load_dwordx4 v[66:69], v202, s[40:41] offset:0
	global_load_dwordx4 v[70:73], v202, s[40:41] offset:16
	global_load_dwordx4 v[74:77], v202, s[40:41] offset:64
	global_load_dwordx4 v[78:81], v202, s[40:41] offset:80
	v_add_u32_e32 v247, 0x18000, v247
	v_add_u32_e32 v202, 0x1000, v202
	global_load_dwordx4 v[166:169], v247, s[30:31] offset:0
	global_load_dwordx4 v[170:173], v247, s[30:31] offset:32
	global_load_dwordx4 v[174:177], v247, s[30:31] offset:64
	global_load_dwordx4 v[178:181], v247, s[30:31] offset:96
	global_load_dwordx4 v[182:185], v247, s[30:31] offset:128
	global_load_dwordx4 v[186:189], v247, s[30:31] offset:160
	global_load_dwordx4 v[98:101], v202, s[40:41] offset:0
	global_load_dwordx4 v[102:105], v202, s[40:41] offset:16
	global_load_dwordx4 v[106:109], v202, s[40:41] offset:64
	global_load_dwordx4 v[110:113], v202, s[40:41] offset:80
	v_mov_b32_e32 v141, 0xf149f2ca
	v_mov_b32_e32 v254, 0
	v_mov_b32_e32 v64, 0
	v_mov_b32_e32 v0, 0
	v_mov_b32_e32 v1, 0
	v_mov_b32_e32 v2, 0
	v_mov_b32_e32 v3, 0
	v_mov_b32_e32 v4, 0
	v_mov_b32_e32 v5, 0
	v_mov_b32_e32 v6, 0
	v_mov_b32_e32 v7, 0
	v_mov_b32_e32 v8, 0
	v_mov_b32_e32 v9, 0
	v_mov_b32_e32 v10, 0
	v_mov_b32_e32 v11, 0
	v_mov_b32_e32 v12, 0
	v_mov_b32_e32 v13, 0
	v_mov_b32_e32 v14, 0
	v_mov_b32_e32 v15, 0
	v_mov_b32_e32 v16, 0
	v_mov_b32_e32 v17, 0
	v_mov_b32_e32 v18, 0
	v_mov_b32_e32 v19, 0
	v_mov_b32_e32 v20, 0
	v_mov_b32_e32 v21, 0
	v_mov_b32_e32 v22, 0
	v_mov_b32_e32 v23, 0
	v_mov_b32_e32 v24, 0
	v_mov_b32_e32 v25, 0
	v_mov_b32_e32 v26, 0
	v_mov_b32_e32 v27, 0
	v_mov_b32_e32 v28, 0
	v_mov_b32_e32 v29, 0
	v_mov_b32_e32 v30, 0
	v_mov_b32_e32 v31, 0
	v_mov_b32_e32 v139, 0xf149f2ca
	v_mov_b32_e32 v255, 0
	v_mov_b32_e32 v134, 0
	v_mov_b32_e32 v32, 0
	v_mov_b32_e32 v33, 0
	v_mov_b32_e32 v34, 0
	v_mov_b32_e32 v35, 0
	v_mov_b32_e32 v36, 0
	v_mov_b32_e32 v37, 0
	v_mov_b32_e32 v38, 0
	v_mov_b32_e32 v39, 0
	v_mov_b32_e32 v40, 0
	v_mov_b32_e32 v41, 0
	v_mov_b32_e32 v42, 0
	v_mov_b32_e32 v43, 0
	v_mov_b32_e32 v44, 0
	v_mov_b32_e32 v45, 0
	v_mov_b32_e32 v46, 0
	v_mov_b32_e32 v47, 0
	v_mov_b32_e32 v48, 0
	v_mov_b32_e32 v49, 0
	v_mov_b32_e32 v50, 0
	v_mov_b32_e32 v51, 0
	v_mov_b32_e32 v52, 0
	v_mov_b32_e32 v53, 0
	v_mov_b32_e32 v54, 0
	v_mov_b32_e32 v55, 0
	v_mov_b32_e32 v56, 0
	v_mov_b32_e32 v57, 0
	v_mov_b32_e32 v58, 0
	v_mov_b32_e32 v59, 0
	v_mov_b32_e32 v60, 0
	v_mov_b32_e32 v61, 0
	v_mov_b32_e32 v62, 0
	v_mov_b32_e32 v63, 0
	s_waitcnt vmcnt(0)
	v_lshlrev_b32_e32 v82, 16, v158
	v_lshlrev_b32_e32 v83, 16, v162
	v_mul_f32_e32 v84, v83, v74
	v_fma_f32 v86, v82, v66, -v84
	v_mul_f32_e32 v84, v83, v66
	v_fma_f32 v87, v82, v74, v84
	v_and_b32_e32 v82, 0xffff0000, v158
	v_and_b32_e32 v83, 0xffff0000, v162
	v_mul_f32_e32 v84, v83, v75
	v_fma_f32 v85, v82, v67, -v84
	v_cvt_pk_bf16_f32 v158, v86, v85
	v_mul_f32_e32 v84, v83, v67
	v_fma_f32 v85, v82, v75, v84
	v_cvt_pk_bf16_f32 v162, v87, v85
	v_lshlrev_b32_e32 v82, 16, v159
	v_lshlrev_b32_e32 v83, 16, v163
	v_mul_f32_e32 v84, v83, v76
	v_fma_f32 v86, v82, v68, -v84
	v_mul_f32_e32 v84, v83, v68
	v_fma_f32 v87, v82, v76, v84
	v_and_b32_e32 v82, 0xffff0000, v159
	v_and_b32_e32 v83, 0xffff0000, v163
	v_mul_f32_e32 v84, v83, v77
	v_fma_f32 v85, v82, v69, -v84
	v_cvt_pk_bf16_f32 v159, v86, v85
	v_mul_f32_e32 v84, v83, v69
	v_fma_f32 v85, v82, v77, v84
	v_cvt_pk_bf16_f32 v163, v87, v85
	v_lshlrev_b32_e32 v82, 16, v160
	v_lshlrev_b32_e32 v83, 16, v164
	v_mul_f32_e32 v84, v83, v78
	v_fma_f32 v86, v82, v70, -v84
	v_mul_f32_e32 v84, v83, v70
	v_fma_f32 v87, v82, v78, v84
	v_and_b32_e32 v82, 0xffff0000, v160
	v_and_b32_e32 v83, 0xffff0000, v164
	v_mul_f32_e32 v84, v83, v79
	v_fma_f32 v85, v82, v71, -v84
	v_cvt_pk_bf16_f32 v160, v86, v85
	v_mul_f32_e32 v84, v83, v71
	v_fma_f32 v85, v82, v79, v84
	v_cvt_pk_bf16_f32 v164, v87, v85
	v_lshlrev_b32_e32 v82, 16, v161
	v_lshlrev_b32_e32 v83, 16, v165
	v_mul_f32_e32 v84, v83, v80
	v_fma_f32 v86, v82, v72, -v84
	v_mul_f32_e32 v84, v83, v72
	v_fma_f32 v87, v82, v80, v84
	v_and_b32_e32 v82, 0xffff0000, v161
	v_and_b32_e32 v83, 0xffff0000, v165
	v_mul_f32_e32 v84, v83, v81
	v_fma_f32 v85, v82, v73, -v84
	v_cvt_pk_bf16_f32 v161, v86, v85
	v_mul_f32_e32 v84, v83, v73
	v_fma_f32 v85, v82, v81, v84
	v_cvt_pk_bf16_f32 v165, v87, v85
	v_lshlrev_b32_e32 v114, 16, v182
	v_lshlrev_b32_e32 v115, 16, v186
	v_mul_f32_e32 v116, v115, v106
	v_fma_f32 v118, v114, v98, -v116
	v_mul_f32_e32 v116, v115, v98
	v_fma_f32 v119, v114, v106, v116
	v_and_b32_e32 v114, 0xffff0000, v182
	v_and_b32_e32 v115, 0xffff0000, v186
	v_mul_f32_e32 v116, v115, v107
	v_fma_f32 v117, v114, v99, -v116
	v_cvt_pk_bf16_f32 v182, v118, v117
	v_mul_f32_e32 v116, v115, v99
	v_fma_f32 v117, v114, v107, v116
	v_cvt_pk_bf16_f32 v186, v119, v117
	v_lshlrev_b32_e32 v114, 16, v183
	v_lshlrev_b32_e32 v115, 16, v187
	v_mul_f32_e32 v116, v115, v108
	v_fma_f32 v118, v114, v100, -v116
	v_mul_f32_e32 v116, v115, v100
	v_fma_f32 v119, v114, v108, v116
	v_and_b32_e32 v114, 0xffff0000, v183
	v_and_b32_e32 v115, 0xffff0000, v187
	v_mul_f32_e32 v116, v115, v109
	v_fma_f32 v117, v114, v101, -v116
	v_cvt_pk_bf16_f32 v183, v118, v117
	v_mul_f32_e32 v116, v115, v101
	v_fma_f32 v117, v114, v109, v116
	v_cvt_pk_bf16_f32 v187, v119, v117
	v_lshlrev_b32_e32 v114, 16, v184
	v_lshlrev_b32_e32 v115, 16, v188
	v_mul_f32_e32 v116, v115, v110
	v_fma_f32 v118, v114, v102, -v116
	v_mul_f32_e32 v116, v115, v102
	v_fma_f32 v119, v114, v110, v116
	v_and_b32_e32 v114, 0xffff0000, v184
	v_and_b32_e32 v115, 0xffff0000, v188
	v_mul_f32_e32 v116, v115, v111
	v_fma_f32 v117, v114, v103, -v116
	v_cvt_pk_bf16_f32 v184, v118, v117
	v_mul_f32_e32 v116, v115, v103
	v_fma_f32 v117, v114, v111, v116
	v_cvt_pk_bf16_f32 v188, v119, v117
	v_lshlrev_b32_e32 v114, 16, v185
	v_lshlrev_b32_e32 v115, 16, v189
	v_mul_f32_e32 v116, v115, v112
	v_fma_f32 v118, v114, v104, -v116
	v_mul_f32_e32 v116, v115, v104
	v_fma_f32 v119, v114, v112, v116
	v_and_b32_e32 v114, 0xffff0000, v185
	v_and_b32_e32 v115, 0xffff0000, v189
	v_mul_f32_e32 v116, v115, v113
	v_fma_f32 v117, v114, v105, -v116
	v_cvt_pk_bf16_f32 v185, v118, v117
	v_mul_f32_e32 v116, v115, v105
	v_fma_f32 v117, v114, v113, v116
	v_cvt_pk_bf16_f32 v189, v119, v117
	s_mov_b32 s18, 0
	s_mov_b32 s19, 0x4000
	s_mov_b32 s22, 0x8000
	s_mov_b32 s16, 0
	s_waitcnt vmcnt(0)
	v_add_u32_e32 v246, s18, v240
	v_add_u32_e32 v245, s18, v241
	ds_write_b128 v246, v[228:231]
	ds_write_b128 v245, v[130:133]
	s_cmp_eq_u64 s[2:3], 0
	s_cbranch_scc1 .LA_swp
; #define SLOAD(i, k0) do { sr_[i].a0 = *reinterpret_cast<const bf16x8*>(&KVh[(size_t)((k0) + sr) * NKV + c16 * 8]); sr_[i].a1 = *reinterpret_cast<const bf16x8*>(&KVh[(size_t)((k0) + 32 + sr) * NKV + c16 * 8]); \
;     sr_[i].rr = *reinterpret_cast<const bf16x8*>(&KR[(size_t)((k0) + rkey) * 32 + rch * 8]); } while (0)
; #define SWRITE(b, i) do { if (isK) { *(bf16x8*)(K_lds + (b) * SHM_K + kst0) = sr_[i].a0; *(bf16x8*)(K_lds + (b) * SHM_K + kst1) = sr_[i].a1; } \
;     else { *(bf16x8*)(V_lds + (b) * SHM_V + vst0) = sr_[i].a0; *(bf16x8*)(V_lds + (b) * SHM_V + vst1) = sr_[i].a1; } \
;     if (rwr) *(bf16x8*)(K_lds + (b) * SHM_K + rst) = sr_[i].rr; } while (0)
; #define SWAIT() asm volatile("s_waitcnt vmcnt(3)" ::: "memory")
; __device__ __forceinline__ void attn_body(const bf16_t* __restrict__ Qb, const bf16_t* __restrict__ KVh, const bf16_t* __restrict__ KR, const float* __restrict__ ropeq,
;                                           bf16_t* __restrict__ Ob, int seq, char* lds, const int tid) {
;     ...
;     SLOAD(SO, KVBLK); if (2 < NT) SLOAD(SE, 2 * KVBLK);
;     SWAIT(); SWRITE(1, SO); __syncthreads();
	v_add_u32_e32 v245, s18, v242
	ds_write_b128 v245, v[248:251] offset:49152
.LA_swp:
	v_add_u32_e32 v247, 0x20000, v243
	global_load_dwordx4 v[228:231], v243, s[28:29]
	global_load_dwordx4 v[130:133], v247, s[28:29]
	global_load_dwordx4 v[248:251], v244, s[44:45]
	s_add_u32 s28, s28, 0x40000
	s_addc_u32 s29, s29, 0
	s_add_u32 s44, s44, 0x1000
	s_addc_u32 s45, s45, 0
	s_waitcnt lgkmcnt(0)
	s_barrier
	s_nop 0
	s_mov_b32 s47, 0x12345678
	s_mov_b32 s47, 0x12345678
	s_mov_b32 s47, 0x12345678

; __device__ __forceinline__ void phase_attn(const Ctx& C, PP p, char* lds_generic) {
;     ...
;     for (int it = C.vcu; it < 2048; it += C.G) {
;         const int qb = it & 15, h = (it >> 4) & 15, b = it >> 8; const size_t t0 = (size_t)b * SEQ, q0 = t0 + qb * 256;
;         __syncthreads();
;         att::attn_body(Q + q0 * NQ + h * 96, KV + t0 * NKV + h * 128, KR + t0 * 32, rope + q0 * 32, O + q0 * DM + h * 64, SEQ, lds_generic, C.tid);
.LA_lexit:
	s_mov_b32 s47, 0
	s_add_i32 s13, s20, s85
	s_cmpk_lt_i32 s13, 0x400
	s_cbranch_scc0 .LA_npf
	s_mov_b32 s47, 1
	s_lshr_b32 s14, s13, 3
	s_and_b32 s14, s14, 15
	s_lshr_b32 s15, s13, 7
	s_lshl_b32 s13, s15, 24
	s_lshl_b32 s14, s14, 8
	s_add_u32 s13, s13, s14
	s_add_u32 s13, s13, 0x10c00000
	s_add_u32 s28, s26, s13
	s_addc_u32 s29, s27, 0
	s_lshl_b32 s13, s15, 18
	s_add_u32 s13, s13, 0x1d400000
	s_add_u32 s44, s26, s13
	s_addc_u32 s45, s27, 0
	v_add_u32_e32 v247, 0x20000, v243
	global_load_dwordx4 v[228:231], v243, s[28:29]
	global_load_dwordx4 v[130:133], v247, s[28:29]
	global_load_dwordx4 v[248:251], v244, s[44:45]
	s_add_u32 s28, s28, 0x40000
	s_addc_u32 s29, s29, 0
	s_add_u32 s44, s44, 0x1000
	s_addc_u32 s45, s45, 0
